# K_FFN epilogue fully hand-written: early conv-weight loads, compact chunk-edge LDS exchange, generated conv+gelu body
# speedup vs baseline: 1.0167x; 1.0099x over previous
; #define LAS __attribute__((address_space(3)))
;     __device__ __forceinline__ void operator()(const f32x4 (&acc)[2][2][4][2], const GUnit& u, int wr, int wc, int fr, int fq, LAS unsigned char* lds) const {
;     ...
;             int fqL = fq, frL = fr; asm volatile("" : "+v"(fqL), "+v"(frL));
;             const int growL = u.pm * 256 + wr * 64 + frL;
;             const int fb = u.pn * 128 + wc * 32 + 8 * fqL;
;             LAS float* EL = (LAS float*)(lds + EDGE_OFF);
; #pragma unroll
;             for (int ai = 0; ai < 2; ++ai) { const int c = 2 * ai + wr;
;                 if (frL == 0) { *(LAS f32x4*)(EL + (c * 2 + 0) * 128 + wc * 32 + 8 * fqL) = acc[ai][1][0][0]; *(LAS f32x4*)(EL + (c * 2 + 0) * 128 + wc * 32 + 8 * fqL + 4) = acc[ai][1][0][1]; }
;                 if (frL == 15) { *(LAS f32x4*)(EL + (c * 2 + 1) * 128 + wc * 32 + 8 * fqL) = acc[ai][1][3][0]; *(LAS f32x4*)(EL + (c * 2 + 1) * 128 + wc * 32 + 8 * fqL + 4) = acc[ai][1][3][1]; } }
;             asm volatile("s_waitcnt lgkmcnt(0)" ::: "memory"); __builtin_amdgcn_s_barrier(); asm volatile("" ::: "memory");
;             f16* A2 = (f16*)(ws + B_VAL); float* GB = (float*)(ws + B_SIDE); float* YP = (float*)(ws + B_SIDE + SIDE_STRIDE); float* VB = (float*)(ws + B_SIDE + 2 * SIDE_STRIDE);
;             const int lane15 = (fqL << 4) | 15, lane0r = (fqL << 4);
;             const int pmod = u.pm & 7;
;             f16x2 w0p[4], w1p[4], w2p[4], bbp[4];
; #pragma unroll
;             for (int n = 0; n < 2; ++n) { const f32x4 a0 = *(const f32x4*)(cw + fb + 4 * n), a1 = *(const f32x4*)(cw + DFF + fb + 4 * n), a2 = *(const f32x4*)(cw + 2 * DFF + fb + 4 * n), ab = *(const f32x4*)(cb + fb + 4 * n);
; #pragma unroll
;                 for (int q = 0; q < 2; ++q) { w0p[2 * n + q] = (f16x2){(f16)a0[2 * q], (f16)a0[2 * q + 1]}; w1p[2 * n + q] = (f16x2){(f16)a1[2 * q], (f16)a1[2 * q + 1]};
;                                               w2p[2 * n + q] = (f16x2){(f16)a2[2 * q], (f16)a2[2 * q + 1]}; bbp[2 * n + q] = (f16x2){(f16)ab[2 * q], (f16)ab[2 * q + 1]}; } }
; #pragma unroll
;             for (int ai = 0; ai < 2; ++ai) { const int c = 2 * ai + wr;
;                 unsigned gp[4][4], eup[4], edp[4];
; #pragma unroll
;                 for (int m = 0; m < 4; ++m)
; #pragma unroll
;                     for (int n = 0; n < 2; ++n)
; #pragma unroll
.LBB0_237:
	s_andn2_b64 vcc, exec, s[8:9]
	s_cbranch_vccnz .LBB0_293
	s_cmp_lg_u32 s70, 8
	s_cbranch_scc1 .LBB0_293
	v_lshlrev_b32_e32 v181, 3, v35
	v_mov_b32_e32 v32, v185
	s_lshl_b32 s8, s34, 7
	v_readlane_b32 s9, v251, 28
	v_readlane_b32 s12, v255, 13
	v_readlane_b32 s13, v255, 14
	s_or_b32 s8, s8, s9
	v_add_u32_e32 v190, s8, v181
	v_ashrrev_i32_e32 v191, 31, v190
	v_lshlrev_b64 v[132:133], 2, v[190:191]
	v_lshl_add_u64 v[134:135], s[12:13], 0, v[132:133]
	v_readlane_b32 s12, v255, 24
	v_readlane_b32 s13, v255, 25
	global_load_dwordx4 v[168:171], v[134:135], off offset:16
	global_load_dwordx4 v[164:167], v[134:135], off
	v_cmp_eq_u32_e64 s[8:9], 15, v32
	v_lshl_add_u64 v[136:137], s[12:13], 0, v[132:133]
	v_readlane_b32 s12, v255, 26
	v_readlane_b32 s13, v255, 27
	global_load_dwordx4 v[160:163], v[136:137], off offset:16
	global_load_dwordx4 v[156:159], v[136:137], off
	v_cmp_eq_u32_e64 s[10:11], 0, v32
	v_lshl_add_u64 v[134:135], s[12:13], 0, v[132:133]
	v_readlane_b32 s12, v255, 22
	v_readlane_b32 s13, v255, 23
	global_load_dwordx4 v[152:155], v[134:135], off offset:16
	global_load_dwordx4 v[148:151], v[134:135], off
	v_lshlrev_b32_e32 v183, 5, v35
	v_lshl_add_u64 v[136:137], s[12:13], 0, v[132:133]
	v_readlane_b32 s12, v251, 50
	v_readlane_b32 s13, v251, 49
	global_load_dwordx4 v[144:147], v[136:137], off offset:16
	global_load_dwordx4 v[140:143], v[136:137], off
	s_and_saveexec_b64 s[80:81], s[10:11]
	v_add_u32_e32 v132, s12, v183
	v_readlane_b32 s12, v251, 51
	v_add_u32_e32 v133, s13, v132
	s_nop 0
	v_add_u32_e32 v132, s12, v132
	ds_write_b128 v133, v[120:123]
	ds_write_b128 v133, v[116:119] offset:16
	ds_write_b128 v132, v[56:59]
	ds_write_b128 v132, v[52:55] offset:16
	s_or_b64 exec, exec, s[80:81]
	v_readlane_b32 s12, v251, 54
	v_readlane_b32 s13, v251, 59
	s_and_saveexec_b64 s[80:81], s[8:9]
	s_nop 0
	v_add_u32_e32 v132, s12, v183
	v_add_u32_e32 v133, s13, v183
	ds_write_b128 v132, v[72:75] offset:512
	ds_write_b128 v132, v[68:71] offset:528
	ds_write_b128 v133, v[4:7] offset:512
	ds_write_b128 v133, v[0:3] offset:528
	s_or_b64 exec, exec, s[80:81]
	v_readlane_b32 s13, v251, 55
	s_waitcnt lgkmcnt(0)
	s_barrier
	v_add_u32_e32 v132, s12, v183
	v_add_u32_e32 v133, s13, v183
	ds_read_b128 v[136:139], v132 offset:1040
	s_cmp_lg_u32 s48, 0
	s_cbranch_scc0 .Lffn_no_eu0
	ds_read_b128 v[172:175], v133
	ds_read_b128 v[176:179], v133 offset:16
	s_branch .Lffn_eu0_done
.Lffn_no_eu0:
	v_mov_b32_e32 v172, 0
	v_mov_b32_e32 v173, 0
	v_mov_b32_e32 v174, 0
	v_mov_b32_e32 v175, 0
	v_mov_b32_e32 v176, 0
	v_mov_b32_e32 v177, 0
	v_mov_b32_e32 v178, 0
	v_mov_b32_e32 v179, 0
;     __device__ __forceinline__ void operator()(const f32x4 (&acc)[2][2][4][2], const GUnit& u, int wr, int wc, int fr, int fq, LAS unsigned char* lds) const {
;     ...
;             for (int n = 0; n < 2; ++n) { const f32x4 a0 = *(const f32x4*)(cw + fb + 4 * n), a1 = *(const f32x4*)(cw + DFF + fb + 4 * n), a2 = *(const f32x4*)(cw + 2 * DFF + fb + 4 * n), ab = *(const f32x4*)(cb + fb + 4 * n);
; #pragma unroll
;                 for (int q = 0; q < 2; ++q) { w0p[2 * n + q] = (f16x2){(f16)a0[2 * q], (f16)a0[2 * q + 1]}; w1p[2 * n + q] = (f16x2){(f16)a1[2 * q], (f16)a1[2 * q + 1]};
;                                               w2p[2 * n + q] = (f16x2){(f16)a2[2 * q], (f16)a2[2 * q + 1]}; bbp[2 * n + q] = (f16x2){(f16)ab[2 * q], (f16)ab[2 * q + 1]}; } }
; #pragma unroll
;             for (int ai = 0; ai < 2; ++ai) { const int c = 2 * ai + wr;
;                 unsigned gp[4][4], eup[4], edp[4];
; #pragma unroll
;                 for (int m = 0; m < 4; ++m)
; #pragma unroll
;                     for (int n = 0; n < 2; ++n)
; #pragma unroll
;                         for (int q = 0; q < 2; ++q) gp[m][2 * n + q] = pk_f16(acc[ai][1][m][n][2 * q], acc[ai][1][m][n][2 * q + 1]);
; #pragma unroll
;                 for (int n = 0; n < 2; ++n) {
;                     const f32x4 eu = c > 0 ? *(const LAS f32x4*)(EL + ((c - 1) * 2 + 1) * 128 + wc * 32 + 8 * fqL + 4 * n) : (f32x4){0.f, 0.f, 0.f, 0.f};
;                     const f32x4 ed = c < 3 ? *(const LAS f32x4*)(EL + ((c + 1) * 2 + 0) * 128 + wc * 32 + 8 * fqL + 4 * n) : (f32x4){0.f, 0.f, 0.f, 0.f};
; #pragma unroll
;                     for (int q = 0; q < 2; ++q) { eup[2 * n + q] = pk_f16(eu[2 * q], eu[2 * q + 1]); edp[2 * n + q] = pk_f16(ed[2 * q], ed[2 * q + 1]); } }
; #pragma unroll
;                 for (int m = 0; m < 4; ++m) {
;                     u32x4 UP, DN, GG;
; #pragma unroll
;                     for (int j = 0; j < 4; ++j) { const int g = (int)gp[m][j];
;                         const int oldu = m > 0 ? shl_((int)gp[m > 0 ? m - 1 : 0][j], lane15) : (int)eup[j];
;                         const int ups = __builtin_amdgcn_update_dpp(0, g, 0x111, 0xf, 0xf, true);
;                         const int oldd = m < 3 ? shl_((int)gp[m < 3 ? m + 1 : 3][j], lane0r) : (int)edp[j];
;                         const int dns = __builtin_amdgcn_update_dpp(0, g, 0x101, 0xf, 0xf, true);
.Lffn_eu0_done:
	ds_read_b128 v[132:135], v132 offset:1024
	s_waitcnt vmcnt(0)
	v_cvt_pk_f16_f32 v164, v164, v165
	v_cvt_pk_f16_f32 v165, v166, v167
	v_cvt_pk_f16_f32 v166, v168, v169
	v_cvt_pk_f16_f32 v167, v170, v171
	v_cvt_pk_f16_f32 v168, v156, v157
	v_cvt_pk_f16_f32 v169, v158, v159
	v_cvt_pk_f16_f32 v170, v160, v161
	v_cvt_pk_f16_f32 v171, v162, v163
	v_cvt_pk_f16_f32 v156, v148, v149
	v_cvt_pk_f16_f32 v157, v150, v151
	v_cvt_pk_f16_f32 v158, v152, v153
	v_cvt_pk_f16_f32 v159, v154, v155
	v_cvt_pk_f16_f32 v160, v140, v141
	v_cvt_pk_f16_f32 v161, v142, v143
	v_cvt_pk_f16_f32 v162, v144, v145
	v_cvt_pk_f16_f32 v163, v146, v147
	s_movk_i32 s45, 0x336a
	s_movk_i32 s55, 0x383f
	s_movk_i32 s65, 0x39b0
	s_mov_b32 s68, 0xb08d
	s_movk_i32 s69, 0x3014
	s_mov_b32 s72, 0xb9c5
	v_cmp_eq_u32_e64 s[8:9], 15, v32
	v_cmp_eq_u32_e64 s[10:11], 0, v32
	s_lshl_b32 s29, s37, 8
	s_add_i32 s29, s29, s48
	v_readlane_b32 s12, v253, 13
	v_readlane_b32 s13, v253, 14
	v_add_u32_e32 v32, s29, v32
	s_movk_i32 s29, 0x1600
	s_and_b32 s36, s37, 7
	v_lshl_add_u64 v[192:193], v[190:191], 1, s[12:13]
	s_waitcnt lgkmcnt(0)
	v_cvt_pk_f16_f32 v172, v172, v173
	v_cvt_pk_f16_f32 v173, v174, v175
	v_cvt_pk_f16_f32 v174, v176, v177
	v_cvt_pk_f16_f32 v175, v178, v179
	v_cvt_pk_f16_f32 v132, v132, v133
	v_cvt_pk_f16_f32 v133, v134, v135
	v_cvt_pk_f16_f32 v134, v136, v137
	v_cvt_pk_f16_f32 v135, v138, v139
	v_cvt_pk_f16_f32 v140, v120, v121
	v_cvt_pk_f16_f32 v141, v122, v123
	v_cvt_pk_f16_f32 v142, v116, v117
	v_cvt_pk_f16_f32 v143, v118, v119
	v_cvt_pk_f16_f32 v144, v104, v105
	v_cvt_pk_f16_f32 v145, v106, v107
	v_cvt_pk_f16_f32 v146, v100, v101
	v_cvt_pk_f16_f32 v147, v102, v103
	v_mov_b32_dpp v172, v140 row_shr:1 row_mask:0xf bank_mask:0xf
	v_mov_b32_dpp v174, v142 row_shr:1 row_mask:0xf bank_mask:0xf
	v_mov_b32_dpp v138, v144 row_ror:15 row_mask:0xf bank_mask:0xf
	v_mov_b32_dpp v178, v146 row_ror:15 row_mask:0xf bank_mask:0xf
	v_mov_b32_dpp v138, v140 row_shl:1 row_mask:0xf bank_mask:0xf
	v_mov_b32_dpp v178, v142 row_shl:1 row_mask:0xf bank_mask:0xf
	v_pk_fma_f16 v136, v172, v164, v160
	v_pk_fma_f16 v176, v174, v166, v162
	v_pk_fma_f16 v136, v140, v168, v136
	v_pk_fma_f16 v176, v142, v170, v176
	v_pk_fma_f16 v136, v138, v156, v136
	v_pk_fma_f16 v176, v178, v158, v176
	v_mov_b32_dpp v173, v141 row_shr:1 row_mask:0xf bank_mask:0xf
	v_mov_b32_dpp v175, v143 row_shr:1 row_mask:0xf bank_mask:0xf
	v_mov_b32_dpp v139, v145 row_ror:15 row_mask:0xf bank_mask:0xf
	v_mov_b32_dpp v179, v147 row_ror:15 row_mask:0xf bank_mask:0xf
	v_mov_b32_dpp v139, v141 row_shl:1 row_mask:0xf bank_mask:0xf
	v_mov_b32_dpp v179, v143 row_shl:1 row_mask:0xf bank_mask:0xf
	v_pk_fma_f16 v137, v173, v165, v161
	v_pk_fma_f16 v177, v175, v167, v163
	v_pk_fma_f16 v137, v141, v169, v137
	v_pk_fma_f16 v177, v143, v171, v177
	v_pk_fma_f16 v137, v139, v157, v137
	v_pk_fma_f16 v177, v179, v159, v177
	s_cmp_eq_u32 s48, 0
	s_cbranch_scc0 .Lffn_side_top_skip
	s_cmp_lg_u32 s36, 0
	s_cbranch_scc0 .Lffn_side_top_skip
	s_and_saveexec_b64 s[80:81], s[10:11]
	s_lshl_b32 s12, s37, 1
	v_mov_b32_e32 v152, 0xb00
	v_mad_i64_i32 v[152:153], vcc, s12, v152, v[190:191]
	v_readlane_b32 s12, v251, 22
	v_readlane_b32 s13, v251, 23
	v_lshlrev_b64 v[152:153], 2, v[152:153]
	s_nop 1
	v_lshl_add_u64 v[154:155], s[12:13], 0, v[152:153]
	global_store_dwordx2 v[154:155], v[120:121], off
	global_store_dwordx2 v[154:155], v[122:123], off offset:8
	global_store_dwordx2 v[154:155], v[116:117], off offset:16
	global_store_dwordx2 v[154:155], v[118:119], off offset:24
	v_readlane_b32 s12, v251, 24
	v_readlane_b32 s13, v251, 25
	v_cvt_f32_f16_e32 v138, v136
	v_cvt_f32_f16_sdwa v139, v136 dst_sel:DWORD dst_unused:UNUSED_PAD src0_sel:WORD_1
	v_lshl_add_u64 v[154:155], s[12:13], 0, v[152:153]
	global_store_dwordx2 v[154:155], v[138:139], off
	v_cvt_f32_f16_e32 v178, v137
	v_cvt_f32_f16_sdwa v179, v137 dst_sel:DWORD dst_unused:UNUSED_PAD src0_sel:WORD_1
	s_nop 0
	global_store_dwordx2 v[154:155], v[178:179], off offset:8
	v_cvt_f32_f16_e32 v138, v176
	v_cvt_f32_f16_sdwa v139, v176 dst_sel:DWORD dst_unused:UNUSED_PAD src0_sel:WORD_1
	s_nop 0
	global_store_dwordx2 v[154:155], v[138:139], off offset:16
	v_cvt_f32_f16_e32 v178, v177
	v_cvt_f32_f16_sdwa v179, v177 dst_sel:DWORD dst_unused:UNUSED_PAD src0_sel:WORD_1
	s_nop 0
	global_store_dwordx2 v[154:155], v[178:179], off offset:24
	v_readlane_b32 s12, v251, 26
	v_readlane_b32 s13, v251, 27
	s_nop 3
	v_lshl_add_u64 v[154:155], s[12:13], 0, v[152:153]
	global_store_dwordx2 v[154:155], v[128:129], off
	global_store_dwordx2 v[154:155], v[130:131], off offset:8
	global_store_dwordx2 v[154:155], v[124:125], off offset:16
	global_store_dwordx2 v[154:155], v[126:127], off offset:24
	s_or_b64 exec, exec, s[80:81]
